# strategy 7.4: user priority 1 for waves 0-3 inside the forgetting-attention and chunk-attention units of the mixer (reset at the work-loop top); waves 4-7 variant was slower
# speedup vs baseline: 1.0054x; 1.0054x over previous
; __device__ __forceinline__ void handoff_wait_one(const unsigned* flag, unsigned val) {
;     if (threadIdx.x == 0) {
;         while (__hip_atomic_load(flag, __ATOMIC_RELAXED, __HIP_MEMORY_SCOPE_AGENT) < val) __builtin_amdgcn_s_sleep(4);
; __device__ void run_phase(const Params& p, unsigned char* lds, int ph) {
;     ...
;             const int it = fetch_item(ctr, lds);
;             if (it >= 3120) break;
;             if (it < 16) { const int bh = it;
;                 fcum_unit(lds, bh, (const float*)(ws + WS_SCAL), p.in[I_FGB] + l * 4, (float*)(ws + WS_F) , (const bf16_t*)(ws + WS_PAB) + (size_t)(bh >> 2) * SEQ * 1536 + 1024 + (bh & 3) * 64, (float*)(ws + WS_KN) + bh * 128, (const bf16_t*)(ws + WS_PAB) + (size_t)(bh >> 2) * SEQ * 1536 + 256 + (bh & 3) * 64, p.in[I_REL] + (size_t)(l * 4 + (bh & 3)) * 320, (float*)(ws + WS_AB) + bh * 2, uflag + 2048 + bh, fval); }
;             else if (it < 48) { const int j = it - 16;
;                 for (int rep = 0; rep < REP_SCAN; ++rep) { scan_unit(lds, j >> 1, j & 1, ws + WS_PREP, (const float*)(ws + WS_EGL), uflag + (j >> 1) * 128, fval); __syncthreads(); } }
;             else if (it < 2096) { const int j = it - 48, n = j >> 4, bh = j & 15, h = bh & 3;
;                 prep_unit(lds, bh, n, (const bf16_t*)(ws + WS_PC), (const float*)(ws + WS_SCAL), p.in[I_CONVW] + (size_t)l * 4 * 1536, p.in[I_ALOG][l * 4 + h], p.in[I_DTB][l * 4 + h],
;                           ws + WS_PREP + (size_t)(bh * 128 + n) * PREP_UNIT, (float*)(ws + WS_EGL), uflag + bh * 128 + n, fval); }
;             else if (it < 2608) { const int j = it - 2096, qb = j & 31, bh = j >> 5, b = bh >> 2, h = bh & 3;
;                 for (int rep = 0; rep < REP_A; ++rep) { attn_unit<1>(lds, b, qb, pab + h * 64, pab + 256 + h * 64, pab + 512 + h * 64, 1536, hbuf + h * 64, DM, nullptr, p.in[I_REL] + (size_t)(l * 4 + h) * 320, (const float*)(ws + WS_AB) + bh * 2, uflag + 2048 + bh, fval); __syncthreads(); } }
;             else { const int j = it - 2608, qb = 31 - (j >> 4), bh = j & 15, b = bh >> 2, h = bh & 3;
;                 for (int rep = 0; rep < REP_FOX; ++rep) { attn_unit<0>(lds, b, qb, pab + 768 + h * 64, pab + 1024 + h * 64, pab + 1280 + h * 64, 1536, hbuf + 256 + h * 64, DM, (const float*)(ws + WS_F) + (size_t)bh * SEQ, nullptr, (const float*)(ws + WS_KN) + bh * 128, uflag + 2048 + bh, fval); __syncthreads(); } }
.Ldp_back3:
	s_nop 0
	s_movk_i32 s0, 0xc30
	s_waitcnt lgkmcnt(0)
	v_add_u32_e32 v2, 32, v90
	v_subrev_u32_e32 v3, 560, v90
	v_cmp_gt_u32_e32 vcc, 576, v90
	s_nop 1
	v_cndmask_b32_e32 v3, v3, v2, vcc
	v_add_u32_e32 v2, -16, v90
	v_cmp_gt_u32_e32 vcc, 592, v2
	s_nop 1
	v_cndmask_b32_e32 v90, v90, v3, vcc
	s_nop 1
	v_cmp_gt_i32_e32 vcc, s0, v90
	s_mov_b64 s[0:1], -1
	s_and_saveexec_b64 s[30:31], vcc
	s_cbranch_execz .LBB0_173
	v_cmp_lt_i32_e32 vcc, 15, v90
	s_and_saveexec_b64 s[0:1], vcc
	s_xor_b64 s[4:5], exec, s[0:1]
	s_cbranch_execz .LBB0_620
	s_mov_b64 s[56:57], s[4:5]
	v_cmp_lt_u32_e32 vcc, 47, v90
	s_and_saveexec_b64 s[0:1], vcc
	s_xor_b64 s[4:5], exec, s[0:1]
	s_cbranch_execz .LBB0_450
	v_writelane_b32 v255, s4, 45
	s_movk_i32 s0, 0x82f
	v_cmp_lt_u32_e32 vcc, s0, v90
	v_writelane_b32 v255, s5, 46
	s_and_saveexec_b64 s[0:1], vcc
	s_xor_b64 s[0:1], exec, s[0:1]
	s_cbranch_execz .LBB0_302
	v_writelane_b32 v255, s0, 47
	s_nop 1
	v_writelane_b32 v255, s1, 48
	s_movk_i32 s0, 0xa2f
	v_cmp_lt_u32_e32 vcc, s0, v90
	s_and_saveexec_b64 s[0:1], vcc
	s_xor_b64 s[0:1], exec, s[0:1]
	v_writelane_b32 v255, s0, 49
	s_nop 1
	v_writelane_b32 v255, s1, 50
	s_cbranch_execz .LBB0_257
	s_branch .Lpr_f
.Lpr_fback:
	v_mov_b32_e32 v146, v212
	s_mov_b64 s[0:1], exec
	v_readlane_b32 s2, v254, 1
	v_readlane_b32 s3, v254, 2
	s_and_b64 s[2:3], s[0:1], s[2:3]
	s_mov_b64 exec, s[2:3]
	s_cbranch_execz .LBB0_186
	v_readlane_b32 s2, v255, 27
	v_lshlrev_b32_e32 v0, 2, v6
	v_readlane_b32 s3, v255, 28
	s_nop 1
	v_lshl_add_u64 v[2:3], s[2:3], 0, v[0:1]
	global_load_dword v0, v[2:3], off sc1
	s_waitcnt vmcnt(0) lgkmcnt(0)
	v_cmp_gt_u32_e32 vcc, s73, v0
	s_and_saveexec_b64 s[2:3], vcc
	s_cbranch_execz .LBB0_185
	s_mov_b64 s[4:5], 0

; __device__ __forceinline__ void handoff_wait_one(const unsigned* flag, unsigned val) {
;     if (threadIdx.x == 0) {
;         while (__hip_atomic_load(flag, __ATOMIC_RELAXED, __HIP_MEMORY_SCOPE_AGENT) < val) __builtin_amdgcn_s_sleep(4);
; __device__ void run_phase(const Params& p, unsigned char* lds, int ph) {
;     ...
;             else if (it < 2608) { const int j = it - 2096, qb = j & 31, bh = j >> 5, b = bh >> 2, h = bh & 3;
;                 for (int rep = 0; rep < REP_A; ++rep) { attn_unit<1>(lds, b, qb, pab + h * 64, pab + 256 + h * 64, pab + 512 + h * 64, 1536, hbuf + h * 64, DM, nullptr, p.in[I_REL] + (size_t)(l * 4 + h) * 320, (const float*)(ws + WS_AB) + bh * 2, uflag + 2048 + bh, fval); __syncthreads(); } }
.LBB0_257:
	v_readlane_b32 s0, v255, 49
	v_readlane_b32 s1, v255, 50
	s_andn2_saveexec_b64 s[10:11], s[0:1]
	s_cbranch_execz .LBB0_301
	s_branch .Lpr_a
	s_nop 0
.Lpr_aback:
	v_lshrrev_b32_e32 v4, 5, v86
	v_mov_b32_e32 v24, v212
	s_mov_b64 s[0:1], exec
	v_readlane_b32 s2, v254, 1
	v_readlane_b32 s3, v254, 2
	s_and_b64 s[2:3], s[0:1], s[2:3]
	s_mov_b64 exec, s[2:3]
	s_cbranch_execz .LBB0_263
	v_readlane_b32 s2, v255, 27
	v_lshlrev_b32_e32 v0, 2, v4
	v_readlane_b32 s3, v255, 28
	s_nop 1
	v_lshl_add_u64 v[2:3], s[2:3], 0, v[0:1]
	global_load_dword v0, v[2:3], off sc1
	s_waitcnt vmcnt(0) lgkmcnt(0)
	v_cmp_gt_u32_e32 vcc, s73, v0
	s_and_saveexec_b64 s[2:3], vcc
	s_cbranch_execz .LBB0_262
	s_mov_b64 s[4:5], 0

; __device__ __forceinline__ void handoff_publish_wt(unsigned* flag, unsigned val) {
;     asm volatile("s_waitcnt vmcnt(0)" ::: "memory");
;     __syncthreads();
;     if (threadIdx.x == 0) __hip_atomic_store(flag, val, __ATOMIC_RELAXED, __HIP_MEMORY_SCOPE_AGENT);
; }
.Ldp_s3:
	s_setprio 0
	v_readlane_b32 s4, v255, 60
	v_readlane_b32 s2, v254, 1
	v_readlane_b32 s3, v254, 2
	s_cmp_eq_u32 s4, 0
	s_cbranch_scc1 .Ldp_none
	s_mov_b64 s[0:1], exec
	s_and_b64 exec, exec, s[2:3]
	s_cbranch_execz .Ldp_rest
	global_store_dword v[250:251], v226, off sc1

; __device__ void run_phase(const Params& p, unsigned char* lds, int ph) {
;     ...
;             else { const int j = it - 2608, qb = 31 - (j >> 4), bh = j & 15, b = bh >> 2, h = bh & 3;
;                 for (int rep = 0; rep < REP_FOX; ++rep) { attn_unit<0>(lds, b, qb, pab + 768 + h * 64, pab + 1024 + h * 64, pab + 1280 + h * 64, 1536, hbuf + 256 + h * 64, DM, (const float*)(ws + WS_F) + (size_t)bh * SEQ, nullptr, (const float*)(ws + WS_KN) + bh * 128, uflag + 2048 + bh, fval); __syncthreads(); } }
.Lpr_f:
	v_readfirstlane_b32 s98, v212
	s_nop 3
	s_cmp_lt_u32 s98, 0x100
	s_cbranch_scc0 .Lpr_f1
	s_setprio 1
.Lpr_f1:
	v_and_b32_e32 v6, 15, v90
	s_branch .Lpr_fback

; __device__ void run_phase(const Params& p, unsigned char* lds, int ph) {
;     ...
;             else if (it < 2608) { const int j = it - 2096, qb = j & 31, bh = j >> 5, b = bh >> 2, h = bh & 3;
.Lpr_a1:
	v_add_u32_e32 v86, 0xfffff7d0, v90
	s_branch .Lpr_aback
